# neighbourhood attention QK: K-fragment LDS prefetch deepened to 2 k-steps ahead (third fragment buffer), as in the dilated loop
# baseline (speedup 1.0000x reference)
;     __device__ __forceinline__ float bias(int qi, int half, int t, int jc) const {
;         const int j = jc + 4 * half;
;         const int r = R + (qi >> 6), c = qi & 63, kr = kr_lo + t, c0 = min(max(c - 8, 0), 48);
;         const bool ok = (j >= c0) && (j < c0 + 16);
;         const int idx = min(max((kr - r + 7) * 31 + (j - c + 15), 0), 15 * 31 - 1);
;         const float bv = rpb[idx];
;         return ok ? bv : -__builtin_inff();
;     }
;     __device__ __forceinline__ void fill(f32x16& S0, f32x16& S1, int qi, int half, int t, int) const {
; #pragma unroll
;         for (int i = 0; i < 16; ++i) { const int jc = 8 * (i >> 2) + (i & 3); S0[i] = bias(qi, half, t, jc); S1[i] = bias(qi, half, t, 32 + jc); }
.LBB0_463:
	s_add_i32 s51, s42, s49
	s_cmp_lt_u32 s51, s46
	s_cselect_b64 vcc, -1, 0
	s_cmp_gt_u32 s51, s47
	s_cselect_b64 s[52:53], -1, 0
	s_or_b64 s[52:53], vcc, s[52:53]
	s_and_b64 vcc, exec, s[52:53]
	s_cbranch_vccnz .LBB0_467
	v_subrev_u32_e32 v2, 59, v172
	v_subrev_u32_e32 v3, 27, v172
	v_subrev_u32_e32 v4, 58, v172
	v_subrev_u32_e32 v5, 26, v172
	v_subrev_u32_e32 v6, 57, v172
	v_subrev_u32_e32 v7, 25, v172
	v_subrev_u32_e32 v8, 56, v172
	v_subrev_u32_e32 v9, 24, v172
	v_med3_i32 v2, v2, 0, v239
	s_add_i32 vcc_lo, 0, 0x18000
	v_med3_i32 v3, v3, 0, v239
	v_med3_i32 v4, v4, 0, v239
	v_med3_i32 v5, v5, 0, v239
	v_med3_i32 v6, v6, 0, v239
	v_med3_i32 v7, v7, 0, v239
	v_med3_i32 v8, v8, 0, v239
	v_med3_i32 v9, v9, 0, v239
	v_readlane_b32 s52, v250, 1
	v_lshl_add_u32 v2, v2, 2, vcc_lo
	v_lshl_add_u32 v3, v3, 2, vcc_lo
	v_lshl_add_u32 v4, v4, 2, vcc_lo
	v_lshl_add_u32 v5, v5, 2, vcc_lo
	v_lshl_add_u32 v6, v6, 2, vcc_lo
	v_lshl_add_u32 v7, v7, 2, vcc_lo
	v_lshl_add_u32 v8, v8, 2, vcc_lo
	v_lshl_add_u32 v9, v9, 2, vcc_lo
	v_readlane_b32 s53, v250, 2
	ds_read_b32 v2, v2
	ds_read_b32 v3, v3
	ds_read_b32 v4, v4
	ds_read_b32 v5, v5
	ds_read_b32 v6, v6
	ds_read_b32 v7, v7
	ds_read_b32 v8, v8
	ds_read_b32 v9, v9
	s_waitcnt lgkmcnt(6)
	v_cndmask_b32_e64 v80, v238, v3, s[52:53]
	v_readlane_b32 s52, v250, 3
	v_readlane_b32 s53, v250, 4
	v_cndmask_b32_e64 v96, v2, v238, s[36:37]
	v_subrev_u32_e32 v2, 51, v172
	s_waitcnt lgkmcnt(5)
	v_cndmask_b32_e64 v97, v4, v238, s[52:53]
	v_readlane_b32 s52, v250, 5
	v_readlane_b32 s53, v250, 6
	v_subrev_u32_e32 v3, 19, v172
	v_subrev_u32_e32 v4, 50, v172
	s_waitcnt lgkmcnt(4)
	v_cndmask_b32_e64 v81, v238, v5, s[52:53]
	v_readlane_b32 s52, v250, 7
	v_readlane_b32 s53, v250, 8
	v_subrev_u32_e32 v5, 18, v172
	v_med3_i32 v2, v2, 0, v239
	s_waitcnt lgkmcnt(3)
	v_cndmask_b32_e64 v98, v6, v238, s[52:53]
	v_readlane_b32 s52, v250, 9
	v_readlane_b32 s53, v250, 10
	v_subrev_u32_e32 v6, 49, v172
	v_med3_i32 v3, v3, 0, v239
	s_waitcnt lgkmcnt(2)
	v_cndmask_b32_e64 v82, v238, v7, s[52:53]
	v_readlane_b32 s52, v250, 11
	v_readlane_b32 s53, v250, 12
	v_subrev_u32_e32 v7, 17, v172
	v_med3_i32 v4, v4, 0, v239
	s_waitcnt lgkmcnt(1)
	v_cndmask_b32_e64 v99, v8, v238, s[52:53]
	v_readlane_b32 s52, v250, 13
	v_readlane_b32 s53, v250, 14
	v_subrev_u32_e32 v8, 48, v172
	v_med3_i32 v5, v5, 0, v239
	s_waitcnt lgkmcnt(0)
	v_cndmask_b32_e64 v83, v238, v9, s[52:53]
	v_add_u32_e32 v9, -16, v172
	v_med3_i32 v6, v6, 0, v239
	v_med3_i32 v7, v7, 0, v239
	v_med3_i32 v8, v8, 0, v239
	v_med3_i32 v9, v9, 0, v239
	v_lshl_add_u32 v2, v2, 2, vcc_lo
	v_lshl_add_u32 v3, v3, 2, vcc_lo
	v_lshl_add_u32 v4, v4, 2, vcc_lo
	v_lshl_add_u32 v5, v5, 2, vcc_lo
	v_lshl_add_u32 v6, v6, 2, vcc_lo
	v_lshl_add_u32 v7, v7, 2, vcc_lo
	v_lshl_add_u32 v8, v8, 2, vcc_lo
	v_lshl_add_u32 v9, v9, 2, vcc_lo
	ds_read_b32 v2, v2
	ds_read_b32 v3, v3
	ds_read_b32 v4, v4
	ds_read_b32 v5, v5
	ds_read_b32 v6, v6
	ds_read_b32 v7, v7
	ds_read_b32 v8, v8
	ds_read_b32 v9, v9
	v_readlane_b32 s52, v250, 15
	v_readlane_b32 s53, v250, 16
	s_waitcnt lgkmcnt(6)
	v_cndmask_b32_e64 v84, v238, v3, s[54:55]
	s_waitcnt lgkmcnt(5)
	v_cndmask_b32_e64 v101, v4, v238, s[56:57]
	v_cndmask_b32_e64 v100, v2, v238, s[52:53]
	s_waitcnt lgkmcnt(4)
	v_cndmask_b32_e64 v85, v238, v5, s[58:59]
	s_waitcnt lgkmcnt(3)
	v_cndmask_b32_e64 v102, v6, v238, s[60:61]
	v_subrev_u32_e32 v2, 43, v172
	v_add_u32_e32 v3, -11, v172
	v_subrev_u32_e32 v4, 42, v172
	v_add_u32_e32 v5, -10, v172
	v_subrev_u32_e32 v6, 41, v172
	s_waitcnt lgkmcnt(2)
	v_cndmask_b32_e64 v86, v238, v7, s[62:63]
	s_waitcnt lgkmcnt(1)
	v_cndmask_b32_e64 v103, v8, v238, s[64:65]
	s_waitcnt lgkmcnt(0)
	v_cndmask_b32_e64 v87, v238, v9, s[40:41]
	v_med3_i32 v2, v2, 0, v239
	v_med3_i32 v3, v3, 0, v239
	v_med3_i32 v4, v4, 0, v239
	v_med3_i32 v5, v5, 0, v239
	v_med3_i32 v6, v6, 0, v239
	v_add_u32_e32 v7, -9, v172
	v_subrev_u32_e32 v8, 40, v172
	v_add_u32_e32 v9, -8, v172
	v_lshl_add_u32 v2, v2, 2, vcc_lo
	v_lshl_add_u32 v3, v3, 2, vcc_lo
	v_lshl_add_u32 v4, v4, 2, vcc_lo
	v_lshl_add_u32 v5, v5, 2, vcc_lo
	v_lshl_add_u32 v6, v6, 2, vcc_lo
	v_med3_i32 v7, v7, 0, v239
	v_med3_i32 v8, v8, 0, v239
	v_med3_i32 v9, v9, 0, v239
	v_lshl_add_u32 v7, v7, 2, vcc_lo
	v_lshl_add_u32 v8, v8, 2, vcc_lo
	v_lshl_add_u32 v9, v9, 2, vcc_lo
	ds_read_b32 v2, v2
	ds_read_b32 v3, v3
	ds_read_b32 v4, v4
	ds_read_b32 v10, v5
	ds_read_b32 v5, v6
	ds_read_b32 v11, v7
	ds_read_b32 v6, v8
	ds_read_b32 v12, v9
	s_waitcnt lgkmcnt(7)
	v_cndmask_b32_e64 v104, v238, v2, s[68:69]
	v_subrev_u32_e32 v2, 35, v172
	v_med3_i32 v2, v2, 0, v239
	s_waitcnt lgkmcnt(1)
	v_cndmask_b32_e64 v107, v238, v6, s[80:81]
	v_lshl_add_u32 v6, v2, 2, vcc_lo
	v_add_u32_e32 v2, -3, v172
	v_med3_i32 v2, v2, 0, v239
	v_lshl_add_u32 v7, v2, 2, vcc_lo
	v_subrev_u32_e32 v2, 34, v172
	v_med3_i32 v2, v2, 0, v239
	v_lshl_add_u32 v8, v2, 2, vcc_lo
	v_add_u32_e32 v2, -2, v172
	v_med3_i32 v2, v2, 0, v239
	v_lshl_add_u32 v9, v2, 2, vcc_lo
	v_subrev_u32_e32 v2, 33, v172
	v_med3_i32 v2, v2, 0, v239
	v_lshl_add_u32 v13, v2, 2, vcc_lo
	v_add_u32_e32 v2, -1, v172
	s_lshl_b32 s51, s50, 15
	v_med3_i32 v2, v2, 0, v239
	s_add_i32 s51, s51, 0
	v_lshl_add_u32 v14, v2, 2, vcc_lo
	v_subrev_u32_e32 v2, 32, v172
	v_add_u32_e32 v0, s51, v145
	v_med3_i32 v2, v2, 0, v239
	v_lshl_add_u32 v15, v2, 2, vcc_lo
	v_med3_i32 v2, v172, 0, v239
	v_add_u32_e32 v90, v0, v156
	v_cndmask_b32_e64 v88, v238, v3, s[70:71]
	v_cndmask_b32_e64 v105, v238, v4, s[72:73]
	v_cndmask_b32_e64 v106, v238, v5, s[76:77]
	v_lshl_add_u32 v89, v2, 2, vcc_lo
	ds_read_b128 v[2:5], v90
	ds_read_b32 v6, v6
	ds_read_b32 v92, v7
	ds_read_b32 v7, v8
	ds_read_b32 v93, v9
	ds_read_b32 v8, v13
	ds_read_b32 v13, v14
	ds_read_b32 v9, v15
	ds_read_b32 v14, v89
	s_waitcnt lgkmcnt(7)
; #define LAS __attribute__((address_space(3)))
; #define MFMA32(a, b, c) __builtin_amdgcn_mfma_f32_32x32x16_bf16((a), (b), (c), 0, 0, 0)
; template <int KSTEPS, class Pol>
; __device__ __forceinline__ void attn_pass(LAS unsigned char* lds, const Pol& P, const bf16_t* qb, int ldq, const bf16_t* kb, int ldk, const bf16_t* vb, int ldv,
;                                           float qs, f32x16 (&O)[4], float& m, float& l) {
;     ...
;         LAS unsigned char* Kb = lds + st * A_STAGE + krow;
;         f32x16 S0, S1;
;         P.fill(S0, S1, qi, half, t, wave);
; #pragma unroll
;         for (int ks = 0; ks < KSTEPS; ++ks) {
;             const int so = ((2 * ks) ^ kx) << 4;
;             const bf16x8 a0 = *(const LAS bf16x8*)(Kb + so);
;             const bf16x8 a1 = *(const LAS bf16x8*)(Kb + 32 * KROWB + so);
;             S0 = MFMA32(a0, qf[ks], S0);
;             S1 = MFMA32(a1, qf[ks], S1);
;         }
;         S0 = S0 * qs; S1 = S1 * qs;
;         float mx = fmaxf(S0[0], S1[0]);
; #pragma unroll
;         for (int i = 1; i < 16; ++i) mx = fmaxf(fmaxf(mx, S0[i]), S1[i]);
;         mx = fmaxf(mx, __shfl_xor(mx, 32));
;         const float mnew = fmaxf(m, mx);
;         const float alpha = __builtin_amdgcn_exp2f(m - mnew);
;         m = mnew;
	v_cndmask_b32_e64 v108, v238, v6, s[84:85]
	s_waitcnt lgkmcnt(5)
	v_cndmask_b32_e64 v109, v238, v7, s[88:89]
	s_waitcnt lgkmcnt(3)
	v_cndmask_b32_e64 v110, v238, v8, s[92:93]
	s_waitcnt lgkmcnt(1)
	v_cndmask_b32_e64 v111, v238, v9, s[96:97]
	ds_read_b128 v[6:9], v90 offset:8192
	v_cndmask_b32_e64 v89, v238, v10, s[74:75]
	v_cndmask_b32_e64 v90, v238, v11, s[78:79]
	v_cndmask_b32_e64 v91, v238, v12, s[82:83]
	v_cndmask_b32_e64 v92, v238, v92, s[86:87]
	v_cndmask_b32_e64 v93, v238, v93, s[90:91]
	v_cndmask_b32_e64 v94, v238, v13, s[94:95]
	s_waitcnt lgkmcnt(1)
	v_cndmask_b32_e64 v95, v238, v14, s[2:3]
	v_mfma_f32_32x32x16_bf16 v[96:111], v[2:5], v[112:115], v[96:111]
	v_and_b32_e32 v15, 64, v234
	v_xor_b32_e32 v14, 32, v234
	v_add_u32_e32 v15, 64, v15
	v_cmp_lt_i32_e32 vcc, v14, v15
	s_nop 1
	v_cndmask_b32_e32 v14, v234, v14, vcc
	s_waitcnt lgkmcnt(0)
	v_mfma_f32_32x32x16_bf16 v[80:95], v[6:9], v[112:115], v[80:95]
	v_add_u32_e32 v6, v0, v157
	ds_read_b128 v[2:5], v6
	ds_read_b128 v[6:9], v6 offset:8192
	v_add_u32_e32 v200, v0, v158
	ds_read_b128 v[192:195], v200
	ds_read_b128 v[196:199], v200 offset:8192
	v_add_u32_e32 v205, v0, v159
	ds_read_b128 v[226:229], v205
	ds_read_b128 v[10:13], v205 offset:8192
	v_lshlrev_b32_e32 v14, 2, v14
	s_waitcnt lgkmcnt(5)
	v_mfma_f32_32x32x16_bf16 v[96:111], v[2:5], v[116:119], v[96:111]
	s_waitcnt lgkmcnt(4)
	v_mfma_f32_32x32x16_bf16 v[80:95], v[6:9], v[116:119], v[80:95]
	v_add_u32_e32 v6, v0, v160
	ds_read_b128 v[2:5], v6
	ds_read_b128 v[6:9], v6 offset:8192
	s_waitcnt lgkmcnt(5)
	v_mfma_f32_32x32x16_bf16 v[96:111], v[192:195], v[120:123], v[96:111]
	s_waitcnt lgkmcnt(4)
	v_mfma_f32_32x32x16_bf16 v[80:95], v[196:199], v[120:123], v[80:95]
	v_add_u32_e32 v200, v0, v161
	ds_read_b128 v[192:195], v200
	ds_read_b128 v[196:199], v200 offset:8192
	s_waitcnt lgkmcnt(5)
	v_mfma_f32_32x32x16_bf16 v[96:111], v[226:229], v[124:127], v[96:111]
	s_waitcnt lgkmcnt(4)
	v_mfma_f32_32x32x16_bf16 v[80:95], v[10:13], v[124:127], v[80:95]
	v_add_u32_e32 v205, v0, v162
	ds_read_b128 v[226:229], v205
	ds_read_b128 v[10:13], v205 offset:8192
	s_waitcnt lgkmcnt(5)
	v_mfma_f32_32x32x16_bf16 v[96:111], v[2:5], v[128:131], v[96:111]
	s_waitcnt lgkmcnt(4)
	v_mfma_f32_32x32x16_bf16 v[80:95], v[6:9], v[128:131], v[80:95]
	v_add_u32_e32 v6, v0, v163
	ds_read_b128 v[2:5], v6
	ds_read_b128 v[6:9], v6 offset:8192
	s_waitcnt lgkmcnt(5)
	v_mfma_f32_32x32x16_bf16 v[96:111], v[192:195], v[132:135], v[96:111]
	s_waitcnt lgkmcnt(4)
	v_mfma_f32_32x32x16_bf16 v[80:95], v[196:199], v[132:135], v[80:95]
	s_waitcnt lgkmcnt(3)
	v_mfma_f32_32x32x16_bf16 v[96:111], v[226:229], v[136:139], v[96:111]
	s_waitcnt lgkmcnt(2)
	v_mfma_f32_32x32x16_bf16 v[80:95], v[10:13], v[136:139], v[80:95]
	s_waitcnt lgkmcnt(1)
	v_mfma_f32_32x32x16_bf16 v[96:111], v[2:5], v[140:143], v[96:111]
	s_waitcnt lgkmcnt(0)
	v_mfma_f32_32x32x16_bf16 v[80:95], v[6:9], v[140:143], v[80:95]
	v_add_u32_e32 v201, s51, v164
	v_add_u32_e32 v202, s51, v165
	v_add_u32_e32 v203, s51, v166
	v_add_u32_e32 v204, s51, v167
	ds_read_b64_tr_b16 v[192:193], v201 offset:16384
	ds_read_b64_tr_b16 v[194:195], v202 offset:2048
	ds_read_b64_tr_b16 v[196:197], v203 offset:16384
	ds_read_b64_tr_b16 v[198:199], v204 offset:2048
	v_add_u32_e32 v2, s51, v168
	v_add_u32_e32 v3, s51, v169
	v_add_u32_e32 v4, s51, v170
	v_add_u32_e32 v5, s51, v171
	ds_read_b64_tr_b16 v[226:227], v2 offset:16384
	ds_read_b64_tr_b16 v[228:229], v3 offset:2048
	v_max_f32_e32 v15, v96, v80
	v_max3_f32 v15, v15, v97, v81
	v_max3_f32 v15, v15, v98, v82
	v_max3_f32 v15, v15, v99, v83
	v_max3_f32 v15, v15, v100, v84
	v_max3_f32 v15, v15, v101, v85
	v_max3_f32 v15, v15, v102, v86
	v_max3_f32 v15, v15, v103, v87
	v_max3_f32 v15, v15, v104, v88
	v_max3_f32 v15, v15, v105, v89
	v_max3_f32 v15, v15, v106, v90
	v_max3_f32 v15, v15, v107, v91
	v_max3_f32 v15, v15, v108, v92
	v_max3_f32 v15, v15, v109, v93
	v_max3_f32 v15, v15, v110, v94
	v_max3_f32 v15, v15, v111, v95
	v_mul_f32_e64 v15, v15, s20
	ds_bpermute_b32 v14, v14, v15
	s_waitcnt lgkmcnt(0)
	v_max3_f32 v0, v175, v15, v14
	v_sub_f32_e32 v14, v175, v0
	v_exp_f32_e32 v14, v14
	s_nop 0
	v_cmp_neq_f32_e32 vcc, 1.0, v14
	s_cbranch_vccz .LBB0_466
	v_pk_mul_f32 v[78:79], v[78:79], v[14:15] op_sel_hi:[1,0]
	v_pk_mul_f32 v[76:77], v[76:77], v[14:15] op_sel_hi:[1,0]
	v_pk_mul_f32 v[74:75], v[74:75], v[14:15] op_sel_hi:[1,0]
	v_pk_mul_f32 v[72:73], v[72:73], v[14:15] op_sel_hi:[1,0]
	v_pk_mul_f32 v[70:71], v[70:71], v[14:15] op_sel_hi:[1,0]
	v_pk_mul_f32 v[68:69], v[68:69], v[14:15] op_sel_hi:[1,0]
	v_pk_mul_f32 v[66:67], v[66:67], v[14:15] op_sel_hi:[1,0]
	v_pk_mul_f32 v[64:65], v[64:65], v[14:15] op_sel_hi:[1,0]
	v_pk_mul_f32 v[62:63], v[62:63], v[14:15] op_sel_hi:[1,0]
	v_pk_mul_f32 v[60:61], v[60:61], v[14:15] op_sel_hi:[1,0]
	v_pk_mul_f32 v[58:59], v[58:59], v[14:15] op_sel_hi:[1,0]
	v_pk_mul_f32 v[56:57], v[56:57], v[14:15] op_sel_hi:[1,0]
	v_pk_mul_f32 v[54:55], v[54:55], v[14:15] op_sel_hi:[1,0]
	v_pk_mul_f32 v[52:53], v[52:53], v[14:15] op_sel_hi:[1,0]
	v_pk_mul_f32 v[50:51], v[50:51], v[14:15] op_sel_hi:[1,0]
	v_pk_mul_f32 v[48:49], v[48:49], v[14:15] op_sel_hi:[1,0]
	v_pk_mul_f32 v[46:47], v[46:47], v[14:15] op_sel_hi:[1,0]
	v_pk_mul_f32 v[44:45], v[44:45], v[14:15] op_sel_hi:[1,0]
	v_pk_mul_f32 v[42:43], v[42:43], v[14:15] op_sel_hi:[1,0]
	v_pk_mul_f32 v[40:41], v[40:41], v[14:15] op_sel_hi:[1,0]
	v_pk_mul_f32 v[38:39], v[38:39], v[14:15] op_sel_hi:[1,0]
	v_pk_mul_f32 v[36:37], v[36:37], v[14:15] op_sel_hi:[1,0]
	v_pk_mul_f32 v[34:35], v[34:35], v[14:15] op_sel_hi:[1,0]
	v_pk_mul_f32 v[32:33], v[32:33], v[14:15] op_sel_hi:[1,0]
	v_pk_mul_f32 v[30:31], v[30:31], v[14:15] op_sel_hi:[1,0]
	v_pk_mul_f32 v[28:29], v[28:29], v[14:15] op_sel_hi:[1,0]
	v_pk_mul_f32 v[26:27], v[26:27], v[14:15] op_sel_hi:[1,0]
	v_pk_mul_f32 v[24:25], v[24:25], v[14:15] op_sel_hi:[1,0]
	v_pk_mul_f32 v[22:23], v[22:23], v[14:15] op_sel_hi:[1,0]
	v_pk_mul_f32 v[20:21], v[20:21], v[14:15] op_sel_hi:[1,0]
	v_pk_mul_f32 v[18:19], v[18:19], v[14:15] op_sel_hi:[1,0]
	v_pk_mul_f32 v[16:17], v[16:17], v[14:15] op_sel_hi:[1,0]
